# attention B/C: speculative softmax - no per-tile overflow pre-check, one l<2^64/finite check per unit with whole-workgroup redo through the original checked loop (slow-path copy)
# speedup vs baseline: 1.0727x; 1.0458x over previous
.LBB0_91:
	s_or_b64 exec, exec, s[2:3]
	s_waitcnt lgkmcnt(0)
	s_barrier
	ds_read_b32 v0, v202
	s_mov_b64 s[2:3], -1
	s_waitcnt lgkmcnt(0)
	s_barrier
	v_cmp_le_i32_e32 vcc, s25, v0
	v_readfirstlane_b32 s12, v0
	s_mov_b32 s98, 0
	s_cbranch_vccnz .LBB0_86
.Lspec_redo_entry:
	s_mov_b32 s99, s12
	s_cmp_lt_i32 s12, 16
	s_mov_b32 s2, s18
	s_cbranch_scc1 .LBB0_96
	s_cmpk_lt_u32 s12, 0x50
	s_mov_b32 s2, s0
	s_cbranch_scc1 .LBB0_96
	s_cmpk_lt_u32 s12, 0x70
	s_mov_b32 s2, s35
	s_cbranch_scc1 .LBB0_96
	s_cmpk_lt_u32 s12, 0xa0
	s_cselect_b32 s2, s34, s19

.LBB0_159:
	s_or_b64 exec, exec, s[14:15]
	global_load_dwordx4 v[124:127], v[10:11], off offset:128
	s_movk_i32 s6, 0xd0
	v_mul_lo_u32 v9, v12, s6
	v_lshl_add_u32 v157, v6, 4, v9
	v_mul_lo_u32 v6, v7, s6
	v_lshl_add_u32 v158, v8, 4, v6
	s_waitcnt vmcnt(3)
	ds_write_b128 v157, v[104:107]
	s_and_saveexec_b64 s[12:13], s[38:39]
	ds_write_b128 v158, v[112:115]
	s_or_b64 exec, exec, s[12:13]
	v_mad_i64_i32 v[6:7], s[12:13], v156, s54, 0
	s_and_b64 s[12:13], s[88:89], exec
	s_cselect_b32 s14, 0x84, 4
	v_lshl_add_u64 v[6:7], s[2:3], 0, v[6:7]
	s_add_u32 s2, s52, s96
	v_lshl_add_u64 v[6:7], v[6:7], 0, v[0:1]
	s_addc_u32 s3, s53, 0
	v_lshl_add_u64 v[150:151], s[2:3], 0, v[6:7]
	s_add_u32 s2, s40, s41
	v_and_b32_e32 v8, 31, v148
	s_addc_u32 s3, s23, 0
	v_mul_u32_u24_e32 v16, 0xd0, v8
	v_lshlrev_b32_e32 v8, 6, v8
	v_cmp_lt_i32_e32 vcc, v207, v206
	s_add_u32 s2, s52, s2
	v_mul_lo_u32 v9, v156, s4
	v_sub_u32_e32 v17, v16, v8
	v_cndmask_b32_e32 v8, v205, v207, vcc
	s_addc_u32 s3, s53, s3
	v_mov_b32_e32 v14, v1
	v_mov_b32_e32 v15, v1
	v_lshl_add_u32 v160, v140, 4, v9
	v_lshlrev_b32_e32 v159, 2, v8
	v_lshl_add_u64 v[152:153], v[2:3], 1, s[2:3]
	v_lshl_add_u64 v[154:155], v[4:5], 1, s[2:3]
	v_mov_b32_e32 v0, v1
	v_mov_b32_e32 v2, v1
	v_mov_b32_e32 v3, v1
	v_mov_b32_e32 v4, v1
	v_mov_b32_e32 v5, v1
	v_mov_b32_e32 v6, v1
	v_mov_b32_e32 v7, v1
	v_mov_b32_e32 v8, v1
	v_mov_b32_e32 v9, v1
	v_mov_b32_e32 v10, v1
	v_mov_b32_e32 v11, v1
	v_mov_b32_e32 v12, v1
	v_mov_b32_e32 v13, v1
	v_add_u32_e32 v164, v16, v130
	v_add_u32_e32 v165, v17, v130
	v_mov_b64_e32 v[30:31], v[14:15]
	v_mov_b64_e32 v[46:47], v[14:15]
	s_mov_b32 s22, 0
	v_mov_b32_e32 v161, 0
	v_bfrev_b32_e32 v218, 1
	v_mov_b32_e32 v219, v218
	v_mov_b32_e32 v220, v218
	v_mov_b32_e32 v221, v218
	v_mov_b32_e32 v222, v218
	v_mov_b32_e32 v223, v218
	v_mov_b32_e32 v224, v218
	v_mov_b32_e32 v225, v218
	v_mov_b32_e32 v226, v218
	v_mov_b32_e32 v227, v218
	v_mov_b32_e32 v228, v218
	v_mov_b32_e32 v229, v218
	v_mov_b32_e32 v230, v218
	v_mov_b32_e32 v231, v218
	v_mov_b32_e32 v232, v218
	v_mov_b32_e32 v233, v218
	v_mov_b64_e32 v[28:29], v[12:13]
	v_mov_b64_e32 v[26:27], v[10:11]
	v_mov_b64_e32 v[24:25], v[8:9]
	v_mov_b64_e32 v[22:23], v[6:7]
	v_mov_b64_e32 v[20:21], v[4:5]
	v_mov_b64_e32 v[18:19], v[2:3]
	v_mov_b64_e32 v[16:17], v[0:1]
	v_mov_b64_e32 v[44:45], v[12:13]
	v_mov_b64_e32 v[42:43], v[10:11]
	v_mov_b64_e32 v[40:41], v[8:9]
	v_mov_b64_e32 v[38:39], v[6:7]
	v_mov_b64_e32 v[36:37], v[4:5]
	v_mov_b64_e32 v[34:35], v[2:3]
	v_mov_b64_e32 v[32:33], v[0:1]
	v_mov_b32_e32 v0, 0
	s_waitcnt vmcnt(2)
	ds_write_b128 v160, v[120:123] offset:13312
	s_waitcnt lgkmcnt(0)
	s_barrier
	s_cmp_lg_u32 s98, 0
	s_cbranch_scc1 .LBB0_162_sl

.LBB0_166:
	ds_read_b128 v[2:5], v164
	ds_read_b128 v[6:9], v164 offset:32
	ds_read_b128 v[10:13], v164 offset:6656
	ds_read_b128 v[128:131], v164 offset:6688
	ds_read_b128 v[132:135], v164 offset:64
	ds_read_b128 v[136:139], v164 offset:96
	ds_read_b128 v[140:143], v164 offset:6720
	ds_read_b128 v[144:147], v164 offset:6752
	ds_read_b128 v[166:169], v164 offset:128
	ds_read_b128 v[170:173], v164 offset:160
	ds_read_b128 v[174:177], v164 offset:6784
	ds_read_b128 v[178:181], v164 offset:6816
	s_cmp_eq_u32 s22, 0
	s_cselect_b64 s[40:41], -1, 0
	s_waitcnt lgkmcnt(11)
	s_nop 0
	v_mfma_f32_32x32x16_bf16 v[64:79], v[2:5], v[80:83], v[218:233]
	s_waitcnt lgkmcnt(9)
	v_mfma_f32_32x32x16_bf16 v[48:63], v[10:13], v[80:83], v[218:233]
	v_mfma_f32_32x32x16_bf16 v[64:79], v[6:9], v[84:87], v[64:79]
	s_waitcnt lgkmcnt(8)
	v_mfma_f32_32x32x16_bf16 v[48:63], v[128:131], v[84:87], v[48:63]
	s_waitcnt lgkmcnt(7)
	v_mfma_f32_32x32x16_bf16 v[64:79], v[132:135], v[88:91], v[64:79]
	s_waitcnt lgkmcnt(5)
	v_mfma_f32_32x32x16_bf16 v[48:63], v[140:143], v[88:91], v[48:63]
	v_mfma_f32_32x32x16_bf16 v[64:79], v[136:139], v[92:95], v[64:79]
	s_waitcnt lgkmcnt(4)
	v_mfma_f32_32x32x16_bf16 v[48:63], v[144:147], v[92:95], v[48:63]
	ds_read_b128 v[144:147], v165 offset:13312
	ds_read_b128 v[140:143], v165 offset:13344
	ds_read_b128 v[136:139], v165 offset:13376
	ds_read_b128 v[132:135], v165 offset:13408
	ds_read_b128 v[128:131], v165 offset:17920
	ds_read_b128 v[10:13], v165 offset:17952
	ds_read_b128 v[2:5], v165 offset:17984
	ds_read_b128 v[6:9], v165 offset:18016
	s_waitcnt lgkmcnt(11)
	v_mfma_f32_32x32x16_bf16 v[64:79], v[166:169], v[96:99], v[64:79]
	s_waitcnt lgkmcnt(9)
	v_mfma_f32_32x32x16_bf16 v[48:63], v[174:177], v[96:99], v[48:63]
	v_mfma_f32_32x32x16_bf16 v[64:79], v[170:173], v[100:103], v[64:79]
	s_waitcnt lgkmcnt(8)
	v_mfma_f32_32x32x16_bf16 v[48:63], v[178:181], v[100:103], v[48:63]
	s_nop 9
	s_and_b64 vcc, exec, s[40:41]
	s_cbranch_vccz .LBB0_168
	s_nop 9
	v_max_f32_e32 v166, v49, v49
	v_max_f32_e32 v167, v65, v65
	v_max_f32_e32 v166, v167, v166
	v_max_f32_e32 v167, v50, v50
	v_max_f32_e32 v168, v66, v66
	v_max_f32_e32 v167, v168, v167
	v_max_f32_e32 v168, v51, v51
	v_max_f32_e32 v169, v67, v67
	v_max3_f32 v166, v64, v48, v166
	v_max_f32_e32 v168, v169, v168
	v_max3_f32 v166, v166, v167, v168
	v_max_f32_e32 v167, v52, v52
	v_max_f32_e32 v168, v68, v68
	v_max_f32_e32 v167, v168, v167
	v_max_f32_e32 v168, v53, v53
	v_max_f32_e32 v169, v69, v69
	v_max_f32_e32 v168, v169, v168
	v_max3_f32 v166, v166, v167, v168
	v_max_f32_e32 v167, v54, v54
	v_max_f32_e32 v168, v70, v70
	v_max_f32_e32 v167, v168, v167
	v_max_f32_e32 v168, v55, v55
	v_max_f32_e32 v169, v71, v71
	v_max_f32_e32 v168, v169, v168
	v_max3_f32 v166, v166, v167, v168
	v_max_f32_e32 v167, v56, v56
	v_max_f32_e32 v168, v72, v72
	v_max_f32_e32 v167, v168, v167
	v_max_f32_e32 v168, v57, v57
	v_max_f32_e32 v169, v73, v73
	v_max_f32_e32 v168, v169, v168
	v_max3_f32 v166, v166, v167, v168
	v_max_f32_e32 v167, v58, v58
	v_max_f32_e32 v168, v74, v74
	v_max_f32_e32 v167, v168, v167
	v_max_f32_e32 v168, v59, v59
	v_max_f32_e32 v169, v75, v75
	v_max_f32_e32 v168, v169, v168
	v_max3_f32 v166, v166, v167, v168
	v_max_f32_e32 v167, v60, v60
	v_max_f32_e32 v168, v76, v76
	v_max_f32_e32 v167, v168, v167
	v_max_f32_e32 v168, v61, v61
	v_max_f32_e32 v169, v77, v77
	v_max_f32_e32 v168, v169, v168
	v_max3_f32 v166, v166, v167, v168
	v_max_f32_e32 v167, v62, v62
	v_max_f32_e32 v168, v78, v78
	v_max_f32_e32 v167, v168, v167
	v_max_f32_e32 v168, v63, v63
	v_max_f32_e32 v169, v79, v79
	v_max_f32_e32 v168, v169, v168
	v_max3_f32 v166, v166, v167, v168
	ds_bpermute_b32 v167, v159, v166
	v_mov_b32_e32 v168, v64
	v_mov_b32_e32 v64, v65
	v_mov_b32_e32 v65, v66
	v_mov_b32_e32 v66, v67
	s_waitcnt lgkmcnt(0)
	v_max_f32_e32 v167, v167, v167
	v_max_f32_e32 v166, v166, v167
	v_max_f32_e32 v167, 0, v166
	v_cndmask_b32_e64 v166, v167, v166, s[40:41]
	v_exp_f32_e64 v167, -v166
	v_mov_b32_e32 v67, v68
	v_mov_b32_e32 v169, v48
	v_add_f32_e32 v161, v161, v166
	v_xor_b32_e32 v218, 0x80000000, v161
	v_mov_b32_e32 v219, v218
	v_mov_b32_e32 v220, v218
	v_mov_b32_e32 v221, v218
	v_mov_b32_e32 v222, v218
	v_mov_b32_e32 v223, v218
	v_mov_b32_e32 v224, v218
	v_mov_b32_e32 v225, v218
	v_mov_b32_e32 v226, v218
	v_mov_b32_e32 v227, v218
	v_mov_b32_e32 v228, v218
	v_mov_b32_e32 v229, v218
	v_mov_b32_e32 v230, v218
	v_mov_b32_e32 v231, v218
	v_mov_b32_e32 v232, v218
	v_mov_b32_e32 v233, v218
	v_pk_add_f32 v[170:171], v[64:65], v[166:167] op_sel_hi:[1,0] neg_lo:[0,1] neg_hi:[0,1]
	v_mov_b32_e32 v65, v50
	v_mov_b32_e32 v50, v51
	v_mov_b32_e32 v51, v52
	v_pk_add_f32 v[172:173], v[66:67], v[166:167] op_sel_hi:[1,0] neg_lo:[0,1] neg_hi:[0,1]
	v_pk_add_f32 v[66:67], v[50:51], v[166:167] op_sel_hi:[1,0] neg_lo:[0,1] neg_hi:[0,1]
	v_mov_b32_e32 v50, v69
	v_mov_b32_e32 v51, v70
	v_pk_add_f32 v[174:175], v[50:51], v[166:167] op_sel_hi:[1,0] neg_lo:[0,1] neg_hi:[0,1]
	v_mov_b32_e32 v50, v53
	v_mov_b32_e32 v51, v54
	v_pk_add_f32 v[68:69], v[50:51], v[166:167] op_sel_hi:[1,0] neg_lo:[0,1] neg_hi:[0,1]
	v_mov_b32_e32 v50, v71
	v_mov_b32_e32 v51, v72
	v_pk_add_f32 v[176:177], v[50:51], v[166:167] op_sel_hi:[1,0] neg_lo:[0,1] neg_hi:[0,1]
	v_mov_b32_e32 v50, v55
	v_mov_b32_e32 v51, v56
	v_pk_add_f32 v[70:71], v[50:51], v[166:167] op_sel_hi:[1,0] neg_lo:[0,1] neg_hi:[0,1]
	v_mov_b32_e32 v50, v73
	v_mov_b32_e32 v51, v74
	v_pk_add_f32 v[178:179], v[50:51], v[166:167] op_sel_hi:[1,0] neg_lo:[0,1] neg_hi:[0,1]
	v_mov_b32_e32 v50, v57
	v_mov_b32_e32 v51, v58
	v_pk_add_f32 v[72:73], v[50:51], v[166:167] op_sel_hi:[1,0] neg_lo:[0,1] neg_hi:[0,1]
	v_mov_b32_e32 v50, v75
	v_mov_b32_e32 v51, v76
	v_pk_add_f32 v[180:181], v[50:51], v[166:167] op_sel_hi:[1,0] neg_lo:[0,1] neg_hi:[0,1]
	v_mov_b32_e32 v50, v59
	v_mov_b32_e32 v51, v60
	v_pk_add_f32 v[74:75], v[50:51], v[166:167] op_sel_hi:[1,0] neg_lo:[0,1] neg_hi:[0,1]
	v_mov_b32_e32 v50, v77
	v_mov_b32_e32 v51, v78
	v_mov_b32_e32 v64, v49
	v_pk_add_f32 v[182:183], v[50:51], v[166:167] op_sel_hi:[1,0] neg_lo:[0,1] neg_hi:[0,1]
	v_mov_b32_e32 v50, v61
	v_mov_b32_e32 v51, v62
	v_cndmask_b32_e64 v48, v167, 1.0, s[40:41]
	v_pk_add_f32 v[168:169], v[168:169], v[166:167] op_sel_hi:[1,0] neg_lo:[0,1] neg_hi:[0,1]
	v_pk_add_f32 v[64:65], v[64:65], v[166:167] op_sel_hi:[1,0] neg_lo:[0,1] neg_hi:[0,1]
	v_pk_add_f32 v[76:77], v[50:51], v[166:167] op_sel_hi:[1,0] neg_lo:[0,1] neg_hi:[0,1]
	v_mul_f32_e32 v0, v0, v48
	v_pk_mul_f32 v[46:47], v[46:47], v[48:49] op_sel_hi:[1,0]
	v_pk_mul_f32 v[44:45], v[44:45], v[48:49] op_sel_hi:[1,0]
	v_pk_mul_f32 v[42:43], v[42:43], v[48:49] op_sel_hi:[1,0]
	v_pk_mul_f32 v[40:41], v[40:41], v[48:49] op_sel_hi:[1,0]
	v_pk_mul_f32 v[38:39], v[38:39], v[48:49] op_sel_hi:[1,0]
	v_pk_mul_f32 v[36:37], v[36:37], v[48:49] op_sel_hi:[1,0]
	v_pk_mul_f32 v[34:35], v[34:35], v[48:49] op_sel_hi:[1,0]
	v_pk_mul_f32 v[32:33], v[32:33], v[48:49] op_sel_hi:[1,0]
	v_pk_mul_f32 v[30:31], v[30:31], v[48:49] op_sel_hi:[1,0]
	v_pk_mul_f32 v[28:29], v[28:29], v[48:49] op_sel_hi:[1,0]
	v_pk_mul_f32 v[26:27], v[26:27], v[48:49] op_sel_hi:[1,0]
	v_pk_mul_f32 v[24:25], v[24:25], v[48:49] op_sel_hi:[1,0]
	v_pk_mul_f32 v[22:23], v[22:23], v[48:49] op_sel_hi:[1,0]
	v_pk_mul_f32 v[20:21], v[20:21], v[48:49] op_sel_hi:[1,0]
	v_pk_mul_f32 v[18:19], v[18:19], v[48:49] op_sel_hi:[1,0]
	v_pk_mul_f32 v[16:17], v[16:17], v[48:49] op_sel_hi:[1,0]
	v_sub_f32_e32 v79, v79, v166
	v_sub_f32_e32 v63, v63, v166
	v_mov_b32_e32 v49, v64
	v_mov_b32_e32 v50, v65
	v_mov_b32_e32 v51, v66
	v_mov_b32_e32 v52, v67
	v_mov_b32_e32 v53, v68
	v_mov_b32_e32 v54, v69
	v_mov_b32_e32 v55, v70
	v_mov_b32_e32 v56, v71
	v_mov_b32_e32 v57, v72
	v_mov_b32_e32 v58, v73
	v_mov_b32_e32 v59, v74
	v_mov_b32_e32 v60, v75
	v_mov_b32_e32 v61, v76
	v_mov_b32_e32 v62, v77
	v_mov_b32_e32 v65, v170
	v_mov_b32_e32 v66, v171
	v_mov_b32_e32 v67, v172
	v_mov_b32_e32 v68, v173
	v_mov_b32_e32 v69, v174
	v_mov_b32_e32 v70, v175
	v_mov_b32_e32 v71, v176
	v_mov_b32_e32 v72, v177
	v_mov_b32_e32 v73, v178
	v_mov_b32_e32 v74, v179
	v_mov_b32_e32 v75, v180
	v_mov_b32_e32 v76, v181
	v_mov_b32_e32 v77, v182
	v_mov_b32_e32 v78, v183
	v_mov_b32_e32 v64, v168
	v_mov_b32_e32 v48, v169

.LBB0_174:
	v_add_f32_e32 v2, 0, v64
	v_add_f32_e32 v3, 0, v48
	v_add_f32_e32 v2, v2, v65
	v_add_f32_e32 v3, v3, v49
	v_add_f32_e32 v2, v66, v2
	v_add_f32_e32 v3, v50, v3
	v_add_f32_e32 v2, v67, v2
	v_add_f32_e32 v3, v51, v3
	v_add_f32_e32 v2, v68, v2
	v_add_f32_e32 v3, v52, v3
	v_add_f32_e32 v2, v69, v2
	v_add_f32_e32 v3, v53, v3
	v_add_f32_e32 v2, v70, v2
	v_add_f32_e32 v3, v54, v3
	v_add_f32_e32 v2, v71, v2
	v_add_f32_e32 v3, v55, v3
	v_add_f32_e32 v2, v72, v2
	v_add_f32_e32 v3, v56, v3
	v_add_f32_e32 v2, v73, v2
	v_add_f32_e32 v3, v57, v3
	v_add_f32_e32 v2, v74, v2
	v_add_f32_e32 v3, v58, v3
	v_add_f32_e32 v2, v75, v2
	v_add_f32_e32 v3, v59, v3
	v_add_f32_e32 v2, v76, v2
	v_add_f32_e32 v3, v60, v3
	v_add_f32_e32 v2, v77, v2
	v_add_f32_e32 v3, v61, v3
	v_add_f32_e32 v2, v78, v2
	v_add_f32_e32 v3, v62, v3
	v_add_f32_e32 v2, v79, v2
	v_add_f32_e32 v3, v63, v3
	v_add_f32_e32 v2, v3, v2
	v_add_f32_e32 v0, v0, v2
	ds_read_b128 v[2:5], v164 offset:22528
	ds_read_b128 v[6:9], v164 offset:22560
	ds_read_b128 v[10:13], v164 offset:29184
	ds_read_b128 v[128:131], v164 offset:29216
	ds_read_b128 v[132:135], v164 offset:22592
	ds_read_b128 v[136:139], v164 offset:22624
	ds_read_b128 v[140:143], v164 offset:29248
	ds_read_b128 v[144:147], v164 offset:29280
	ds_read_b128 v[166:169], v164 offset:22656
	ds_read_b128 v[170:173], v164 offset:22688
	ds_read_b128 v[174:177], v164 offset:29312
	ds_read_b128 v[178:181], v164 offset:29344
	s_waitcnt lgkmcnt(11)
	s_nop 0
	v_mfma_f32_32x32x16_bf16 v[64:79], v[2:5], v[80:83], v[218:233]
	s_waitcnt lgkmcnt(9)
	v_mfma_f32_32x32x16_bf16 v[48:63], v[10:13], v[80:83], v[218:233]
	v_mfma_f32_32x32x16_bf16 v[64:79], v[6:9], v[84:87], v[64:79]
	s_waitcnt lgkmcnt(8)
	v_mfma_f32_32x32x16_bf16 v[48:63], v[128:131], v[84:87], v[48:63]
	s_waitcnt lgkmcnt(7)
	v_mfma_f32_32x32x16_bf16 v[64:79], v[132:135], v[88:91], v[64:79]
	s_waitcnt lgkmcnt(5)
	v_mfma_f32_32x32x16_bf16 v[48:63], v[140:143], v[88:91], v[48:63]
	v_mfma_f32_32x32x16_bf16 v[64:79], v[136:139], v[92:95], v[64:79]
	s_waitcnt lgkmcnt(4)
	v_mfma_f32_32x32x16_bf16 v[48:63], v[144:147], v[92:95], v[48:63]
	ds_read_b128 v[144:147], v165 offset:35840
	ds_read_b128 v[140:143], v165 offset:35872
	ds_read_b128 v[136:139], v165 offset:35904
	ds_read_b128 v[132:135], v165 offset:35936
	ds_read_b128 v[128:131], v165 offset:40448
	ds_read_b128 v[10:13], v165 offset:40480
	ds_read_b128 v[2:5], v165 offset:40512
	ds_read_b128 v[6:9], v165 offset:40544
	s_waitcnt lgkmcnt(11)
	v_mfma_f32_32x32x16_bf16 v[64:79], v[166:169], v[96:99], v[64:79]
	s_waitcnt lgkmcnt(9)
	v_mfma_f32_32x32x16_bf16 v[48:63], v[174:177], v[96:99], v[48:63]
	v_mfma_f32_32x32x16_bf16 v[64:79], v[170:173], v[100:103], v[64:79]
	s_waitcnt lgkmcnt(8)
	v_mfma_f32_32x32x16_bf16 v[48:63], v[178:181], v[100:103], v[48:63]
	s_nop 10

.LBB0_180:
	v_add_f32_e32 v2, 0, v14
	v_add_f32_e32 v3, 0, v15
	v_add_f32_e32 v2, v2, v48
	v_add_f32_e32 v3, v3, v49
	v_add_f32_e32 v2, v64, v2
	v_add_f32_e32 v3, v50, v3
	v_add_f32_e32 v2, v65, v2
	v_add_f32_e32 v3, v51, v3
	v_add_f32_e32 v2, v66, v2
	v_add_f32_e32 v3, v52, v3
	v_add_f32_e32 v2, v67, v2
	v_add_f32_e32 v3, v53, v3
	v_add_f32_e32 v2, v68, v2
	v_add_f32_e32 v3, v54, v3
	v_add_f32_e32 v2, v69, v2
	v_add_f32_e32 v3, v55, v3
	v_add_f32_e32 v2, v70, v2
	v_add_f32_e32 v3, v56, v3
	v_add_f32_e32 v2, v71, v2
	v_add_f32_e32 v3, v57, v3
	v_add_f32_e32 v2, v72, v2
	v_add_f32_e32 v3, v58, v3
	v_add_f32_e32 v2, v73, v2
	v_add_f32_e32 v3, v59, v3
	v_add_f32_e32 v2, v74, v2
	v_add_f32_e32 v3, v60, v3
	v_add_f32_e32 v2, v75, v2
	v_add_f32_e32 v3, v61, v3
	v_add_f32_e32 v2, v76, v2
	v_add_f32_e32 v3, v62, v3
	v_add_f32_e32 v2, v77, v2
	v_add_f32_e32 v3, v63, v3
	v_add_f32_e32 v2, v3, v2
	v_add_f32_e32 v0, v0, v2
	v_lshl_add_u64 v[150:151], v[150:151], 0, s[30:31]
	v_lshl_add_u64 v[152:153], v[152:153], 0, s[26:27]
	s_andn2_b64 vcc, exec, s[90:91]
	v_lshl_add_u64 v[154:155], v[154:155], 0, s[26:27]
	s_waitcnt lgkmcnt(0)
	s_barrier
	s_cbranch_vccz .LBB0_203
	s_mov_b32 s22, s15
	s_branch .LBB0_162
.LBB0_162_sl:
	s_add_i32 s15, s22, 2
	s_cmp_lt_u32 s15, s14
	s_cselect_b64 s[2:3], -1, 0
	s_cmp_ge_u32 s15, s14
	s_cselect_b64 s[90:91], -1, 0
	s_and_b64 vcc, exec, s[90:91]
	v_lshl_add_u64 v[14:15], v[152:153], 0, s[20:21]
	s_cbranch_vccnz .LBB0_166_sl
	v_add_co_u32_e32 v2, vcc, 0x9183000, v14
	s_nop 1
	v_addc_co_u32_e32 v3, vcc, 0, v15, vcc
	global_load_dwordx4 v[104:107], v[2:3], off offset:2048
	s_and_saveexec_b64 s[12:13], s[38:39]
	s_cbranch_execz .LBB0_165_sl
	v_lshl_add_u64 v[2:3], v[154:155], 0, s[20:21]
	v_add_co_u32_e32 v2, vcc, 0x9183000, v2
	s_nop 1
	v_addc_co_u32_e32 v3, vcc, 0, v3, vcc
	global_load_dwordx4 v[112:115], v[2:3], off offset:2048

.LBB0_184:
	s_lshl_b32 s2, s64, 2
	s_add_i32 s2, s2, s33
	s_mul_i32 s40, s2, 0x108000
	s_mul_hi_i32 s41, s2, 0x108000
	s_add_u32 s12, s77, s40
	s_addc_u32 s13, s71, s41
	s_add_u32 s22, s72, s40
	v_ashrrev_i32_e32 v0, 31, v148
	s_addc_u32 s23, s66, s41
	v_lshrrev_b32_e32 v0, 29, v0
	s_add_u32 s14, s24, s40
	v_add_u32_e32 v0, v148, v0
	s_addc_u32 s15, s76, s41
	v_ashrrev_i32_e32 v26, 3, v0
	v_and_b32_e32 v0, -8, v0
	s_and_b64 s[2:3], s[88:89], exec
	v_sub_u32_e32 v27, v148, v0
	v_lshlrev_b32_e32 v0, 6, v26
	s_cselect_b32 s3, 0, 0x2000
	v_lshl_add_u32 v2, v27, 3, v0
	v_mov_b64_e32 v[4:5], s[14:15]
	v_lshlrev_b32_e32 v0, 4, v148
	s_cselect_b32 s2, 0x84, 4
	v_mad_i64_i32 v[4:5], s[14:15], v156, s54, v[4:5]
	v_and_b32_e32 v18, 0x70, v0
	v_mov_b32_e32 v19, v1
	s_lshl_b32 s38, s3, 7
	v_lshl_add_u64 v[4:5], v[4:5], 0, v[18:19]
	s_add_u32 s14, s22, s38
	v_ashrrev_i32_e32 v3, 31, v2
	v_lshrrev_b32_e32 v6, 1, v148
	v_and_b32_e32 v19, 31, v148
	s_addc_u32 s15, s23, 0
	v_lshlrev_b64 v[20:21], 1, v[2:3]
	v_and_or_b32 v0, v6, s5, v19
	v_lshl_add_u64 v[2:3], s[14:15], 0, v[20:21]
	s_lshl_b32 s96, s3, 1
	v_and_b32_e32 v22, 0xffffffe0, v156
	v_add_lshl_u32 v0, v0, s65, 7
	v_lshl_add_u64 v[4:5], v[4:5], 0, s[96:97]
	global_load_dwordx4 v[66:69], v[2:3], off
	global_load_dwordx4 v[78:81], v[4:5], off
	v_lshl_add_u64 v[2:3], s[12:13], 0, v[0:1]
	v_ashrrev_i32_e32 v23, 31, v22
	s_or_b32 s3, s38, 0x2000
	v_lshl_add_u64 v[2:3], v[22:23], 1, v[2:3]
	v_and_b32_e32 v0, 16, v6
	s_add_u32 s12, s22, s3
	v_lshl_add_u64 v[2:3], v[2:3], 0, v[0:1]
	s_addc_u32 s13, s23, 0
	global_load_dwordx4 v[70:73], v[2:3], off
	global_load_dwordx4 v[74:77], v[2:3], off offset:32
	v_lshl_add_u64 v[2:3], s[12:13], 0, v[20:21]
	global_load_dwordx4 v[86:89], v[4:5], off offset:128
	global_load_dwordx4 v[82:85], v[2:3], off
	v_mad_i64_i32 v[24:25], s[12:13], v156, s54, 0
	v_mad_u64_u32 v[122:123], s[12:13], v156, s4, v[18:19]
	s_add_u32 s12, s36, s96
	v_or_b32_e32 v24, v24, v18
	s_addc_u32 s13, s37, 0
	v_cmp_lt_i32_e32 vcc, v207, v206
	s_waitcnt vmcnt(14)
	v_lshl_add_u64 v[124:125], s[12:13], 0, v[24:25]
	s_add_u32 s12, s36, s38
	v_cndmask_b32_e32 v23, v205, v207, vcc
	v_mul_u32_u24_e32 v133, 0x90, v19
	v_mul_lo_u32 v18, v26, s4
	v_lshl_or_b32 v34, v22, 1, v0
	s_addc_u32 s13, s37, 0
	s_mov_b32 s3, 3
	v_mov_b32_e32 v2, v1
	v_mov_b32_e32 v3, v1
	v_mov_b32_e32 v4, v1
	v_mov_b32_e32 v5, v1
	v_mov_b32_e32 v6, v1
	v_mov_b32_e32 v7, v1
	v_mov_b32_e32 v8, v1
	v_mov_b32_e32 v9, v1
	v_mov_b32_e32 v10, v1
	v_mov_b32_e32 v11, v1
	v_mov_b32_e32 v12, v1
	v_mov_b32_e32 v13, v1
	v_mov_b32_e32 v14, v1
	v_mov_b32_e32 v15, v1
	v_mov_b32_e32 v16, v1
	v_mov_b32_e32 v17, v1
	v_lshlrev_b32_e32 v132, 2, v23
	v_lshl_add_u32 v123, v27, 4, v18
	v_lshl_add_u64 v[126:127], s[12:13], 0, v[20:21]
	v_mov_b32_e32 v18, v1
	v_mov_b32_e32 v19, v1
	v_mov_b32_e32 v20, v1
	v_mov_b32_e32 v21, v1
	v_mov_b32_e32 v22, v1
	v_mov_b32_e32 v23, v1
	v_mov_b32_e32 v24, v1
	v_mov_b32_e32 v25, v1
	v_mov_b32_e32 v26, v1
	v_mov_b32_e32 v27, v1
	v_mov_b32_e32 v28, v1
	v_mov_b32_e32 v29, v1
	v_mov_b32_e32 v30, v1
	v_mov_b32_e32 v31, v1
	v_mov_b32_e32 v32, v1
	v_mov_b32_e32 v33, v1
	v_mov_b32_e32 v134, 0
	v_bfrev_b32_e32 v218, 1
	v_mov_b32_e32 v219, v218
	v_mov_b32_e32 v220, v218
	v_mov_b32_e32 v221, v218
	v_mov_b32_e32 v222, v218
	v_mov_b32_e32 v223, v218
	v_mov_b32_e32 v224, v218
	v_mov_b32_e32 v225, v218
	v_mov_b32_e32 v226, v218
	v_mov_b32_e32 v227, v218
	v_mov_b32_e32 v228, v218
	v_mov_b32_e32 v229, v218
	v_mov_b32_e32 v230, v218
	v_mov_b32_e32 v231, v218
	v_mov_b32_e32 v232, v218
	v_mov_b32_e32 v233, v218
	v_add_u32_e32 v135, v133, v34
	v_mov_b32_e32 v136, 0
	s_waitcnt vmcnt(5)
	ds_write_b128 v123, v[66:69]
	s_waitcnt vmcnt(4)
	ds_write_b128 v122, v[78:81] offset:9216
	s_waitcnt lgkmcnt(0)
	s_barrier
	s_cmp_lg_u32 s98, 0
	s_cbranch_scc1 .LBB0_186_sl
	s_branch .LBB0_186

.LBB0_188:
	ds_read_b128 v[90:93], v135
	ds_read_b128 v[94:97], v135 offset:32
	ds_read_b128 v[98:101], v135 offset:4608
	ds_read_b128 v[138:141], v135 offset:4640
	s_cmp_eq_u32 s3, 3
	s_cselect_b64 s[38:39], -1, 0
	s_waitcnt vmcnt(3) lgkmcnt(3)
	s_nop 0
	v_mfma_f32_32x32x16_bf16 v[50:65], v[90:93], v[70:73], v[218:233]
	v_add_u32_e32 v137, v133, v0
	s_waitcnt lgkmcnt(1)
	v_mfma_f32_32x32x16_bf16 v[34:49], v[98:101], v[70:73], v[218:233]
	s_waitcnt vmcnt(2)
	v_mfma_f32_32x32x16_bf16 v[50:65], v[94:97], v[74:77], v[50:65]
	ds_read_b128 v[118:121], v137 offset:9216
	ds_read_b128 v[114:117], v137 offset:9248
	ds_read_b128 v[110:113], v137 offset:9280
	ds_read_b128 v[106:109], v137 offset:9312
	ds_read_b128 v[102:105], v137 offset:13824
	ds_read_b128 v[98:101], v137 offset:13856
	ds_read_b128 v[90:93], v137 offset:13888
	ds_read_b128 v[94:97], v137 offset:13920
	s_waitcnt lgkmcnt(8)
	v_mfma_f32_32x32x16_bf16 v[34:49], v[138:141], v[74:77], v[34:49]
	s_nop 1
	s_and_b64 vcc, exec, s[38:39]
	s_cbranch_vccz .LBB0_190
	s_nop 9
	v_max_f32_e32 v138, v35, v35
	v_max_f32_e32 v139, v51, v51
	v_max_f32_e32 v138, v139, v138
	v_max_f32_e32 v139, v36, v36
	v_max_f32_e32 v140, v52, v52
	v_max_f32_e32 v139, v140, v139
	v_max_f32_e32 v140, v37, v37
	v_max_f32_e32 v141, v53, v53
	v_max3_f32 v138, v50, v34, v138
	v_max_f32_e32 v140, v141, v140
	v_max3_f32 v138, v138, v139, v140
	v_max_f32_e32 v139, v38, v38
	v_max_f32_e32 v140, v54, v54
	v_max_f32_e32 v139, v140, v139
	v_max_f32_e32 v140, v39, v39
	v_max_f32_e32 v141, v55, v55
	v_max_f32_e32 v140, v141, v140
	v_max3_f32 v138, v138, v139, v140
	v_max_f32_e32 v139, v40, v40
	v_max_f32_e32 v140, v56, v56
	v_max_f32_e32 v139, v140, v139
	v_max_f32_e32 v140, v41, v41
	v_max_f32_e32 v141, v57, v57
	v_max_f32_e32 v140, v141, v140
	v_max3_f32 v138, v138, v139, v140
	v_max_f32_e32 v139, v42, v42
	v_max_f32_e32 v140, v58, v58
	v_max_f32_e32 v139, v140, v139
	v_max_f32_e32 v140, v43, v43
	v_max_f32_e32 v141, v59, v59
	v_max_f32_e32 v140, v141, v140
	v_max3_f32 v138, v138, v139, v140
	v_max_f32_e32 v139, v44, v44
	v_max_f32_e32 v140, v60, v60
	v_max_f32_e32 v139, v140, v139
	v_max_f32_e32 v140, v45, v45
	v_max_f32_e32 v141, v61, v61
	v_max_f32_e32 v140, v141, v140
	v_max3_f32 v138, v138, v139, v140
	v_max_f32_e32 v139, v46, v46
	v_max_f32_e32 v140, v62, v62
	v_max_f32_e32 v139, v140, v139
	v_max_f32_e32 v140, v47, v47
	v_max_f32_e32 v141, v63, v63
	v_max_f32_e32 v140, v141, v140
	v_max3_f32 v138, v138, v139, v140
	v_max_f32_e32 v139, v48, v48
	v_max_f32_e32 v140, v64, v64
	v_max_f32_e32 v139, v140, v139
	v_max_f32_e32 v140, v49, v49
	v_max_f32_e32 v141, v65, v65
	v_max_f32_e32 v140, v141, v140
	v_max3_f32 v138, v138, v139, v140
	ds_bpermute_b32 v139, v132, v138
	v_mov_b32_e32 v140, v50
	v_mov_b32_e32 v50, v51
	v_mov_b32_e32 v51, v52
	v_mov_b32_e32 v52, v53
	s_waitcnt lgkmcnt(0)
	v_max_f32_e32 v139, v139, v139
	v_max_f32_e32 v138, v138, v139
	v_max_f32_e32 v139, 0, v138
	v_cndmask_b32_e64 v138, v139, v138, s[38:39]
	v_exp_f32_e64 v139, -v138
	v_mov_b32_e32 v53, v54
	v_mov_b32_e32 v141, v34
	v_add_f32_e32 v134, v134, v138
	v_xor_b32_e32 v218, 0x80000000, v134
	v_mov_b32_e32 v219, v218
	v_mov_b32_e32 v220, v218
	v_mov_b32_e32 v221, v218
	v_mov_b32_e32 v222, v218
	v_mov_b32_e32 v223, v218
	v_mov_b32_e32 v224, v218
	v_mov_b32_e32 v225, v218
	v_mov_b32_e32 v226, v218
	v_mov_b32_e32 v227, v218
	v_mov_b32_e32 v228, v218
	v_mov_b32_e32 v229, v218
	v_mov_b32_e32 v230, v218
	v_mov_b32_e32 v231, v218
	v_mov_b32_e32 v232, v218
	v_mov_b32_e32 v233, v218
	v_pk_add_f32 v[142:143], v[50:51], v[138:139] op_sel_hi:[1,0] neg_lo:[0,1] neg_hi:[0,1]
	v_mov_b32_e32 v51, v36
	v_mov_b32_e32 v36, v37
	v_mov_b32_e32 v37, v38
	v_pk_add_f32 v[144:145], v[52:53], v[138:139] op_sel_hi:[1,0] neg_lo:[0,1] neg_hi:[0,1]
	v_pk_add_f32 v[52:53], v[36:37], v[138:139] op_sel_hi:[1,0] neg_lo:[0,1] neg_hi:[0,1]
	v_mov_b32_e32 v36, v55
	v_mov_b32_e32 v37, v56
	v_pk_add_f32 v[146:147], v[36:37], v[138:139] op_sel_hi:[1,0] neg_lo:[0,1] neg_hi:[0,1]
	v_mov_b32_e32 v36, v39
	v_mov_b32_e32 v37, v40
	v_pk_add_f32 v[54:55], v[36:37], v[138:139] op_sel_hi:[1,0] neg_lo:[0,1] neg_hi:[0,1]
	v_mov_b32_e32 v36, v57
	v_mov_b32_e32 v37, v58
	v_pk_add_f32 v[150:151], v[36:37], v[138:139] op_sel_hi:[1,0] neg_lo:[0,1] neg_hi:[0,1]
	v_mov_b32_e32 v36, v41
	v_mov_b32_e32 v37, v42
	v_pk_add_f32 v[56:57], v[36:37], v[138:139] op_sel_hi:[1,0] neg_lo:[0,1] neg_hi:[0,1]
	v_mov_b32_e32 v36, v59
	v_mov_b32_e32 v37, v60
	v_pk_add_f32 v[152:153], v[36:37], v[138:139] op_sel_hi:[1,0] neg_lo:[0,1] neg_hi:[0,1]
	v_mov_b32_e32 v36, v43
	v_mov_b32_e32 v37, v44
	v_pk_add_f32 v[58:59], v[36:37], v[138:139] op_sel_hi:[1,0] neg_lo:[0,1] neg_hi:[0,1]
	v_mov_b32_e32 v36, v61
	v_mov_b32_e32 v37, v62
	v_pk_add_f32 v[154:155], v[36:37], v[138:139] op_sel_hi:[1,0] neg_lo:[0,1] neg_hi:[0,1]
	v_mov_b32_e32 v36, v45
	v_mov_b32_e32 v37, v46
	v_pk_add_f32 v[60:61], v[36:37], v[138:139] op_sel_hi:[1,0] neg_lo:[0,1] neg_hi:[0,1]
	v_mov_b32_e32 v36, v63
	v_mov_b32_e32 v37, v64
	v_mov_b32_e32 v50, v35
	v_pk_add_f32 v[156:157], v[36:37], v[138:139] op_sel_hi:[1,0] neg_lo:[0,1] neg_hi:[0,1]
	v_mov_b32_e32 v36, v47
	v_mov_b32_e32 v37, v48
	v_cndmask_b32_e64 v34, v139, 1.0, s[38:39]
	v_pk_add_f32 v[140:141], v[140:141], v[138:139] op_sel_hi:[1,0] neg_lo:[0,1] neg_hi:[0,1]
	v_pk_add_f32 v[50:51], v[50:51], v[138:139] op_sel_hi:[1,0] neg_lo:[0,1] neg_hi:[0,1]
	v_pk_add_f32 v[62:63], v[36:37], v[138:139] op_sel_hi:[1,0] neg_lo:[0,1] neg_hi:[0,1]
	v_mul_f32_e32 v136, v136, v34
	v_sub_f32_e32 v65, v65, v138
	v_sub_f32_e32 v49, v49, v138
	v_pk_mul_f32 v[32:33], v[32:33], v[34:35] op_sel_hi:[1,0]
	v_pk_mul_f32 v[30:31], v[30:31], v[34:35] op_sel_hi:[1,0]
	v_pk_mul_f32 v[28:29], v[28:29], v[34:35] op_sel_hi:[1,0]
	v_pk_mul_f32 v[26:27], v[26:27], v[34:35] op_sel_hi:[1,0]
	v_pk_mul_f32 v[24:25], v[24:25], v[34:35] op_sel_hi:[1,0]
	v_pk_mul_f32 v[22:23], v[22:23], v[34:35] op_sel_hi:[1,0]
	v_pk_mul_f32 v[20:21], v[20:21], v[34:35] op_sel_hi:[1,0]
	v_pk_mul_f32 v[18:19], v[18:19], v[34:35] op_sel_hi:[1,0]
	v_pk_mul_f32 v[16:17], v[16:17], v[34:35] op_sel_hi:[1,0]
	v_pk_mul_f32 v[14:15], v[14:15], v[34:35] op_sel_hi:[1,0]
	v_pk_mul_f32 v[12:13], v[12:13], v[34:35] op_sel_hi:[1,0]
	v_pk_mul_f32 v[10:11], v[10:11], v[34:35] op_sel_hi:[1,0]
	v_pk_mul_f32 v[8:9], v[8:9], v[34:35] op_sel_hi:[1,0]
	v_pk_mul_f32 v[6:7], v[6:7], v[34:35] op_sel_hi:[1,0]
	v_pk_mul_f32 v[4:5], v[4:5], v[34:35] op_sel_hi:[1,0]
	v_pk_mul_f32 v[2:3], v[2:3], v[34:35] op_sel_hi:[1,0]
	v_mov_b32_e32 v35, v50
	v_mov_b32_e32 v36, v51
	v_mov_b32_e32 v37, v52
	v_mov_b32_e32 v38, v53
	v_mov_b32_e32 v39, v54
	v_mov_b32_e32 v40, v55
	v_mov_b32_e32 v41, v56
	v_mov_b32_e32 v42, v57
	v_mov_b32_e32 v43, v58
	v_mov_b32_e32 v44, v59
	v_mov_b32_e32 v45, v60
	v_mov_b32_e32 v46, v61
	v_mov_b32_e32 v47, v62
	v_mov_b32_e32 v48, v63
	v_mov_b32_e32 v51, v142
	v_mov_b32_e32 v52, v143
	v_mov_b32_e32 v53, v144
	v_mov_b32_e32 v54, v145
	v_mov_b32_e32 v55, v146
	v_mov_b32_e32 v56, v147
	v_mov_b32_e32 v57, v150
	v_mov_b32_e32 v58, v151
	v_mov_b32_e32 v59, v152
	v_mov_b32_e32 v60, v153
	v_mov_b32_e32 v61, v154
	v_mov_b32_e32 v62, v155
	v_mov_b32_e32 v63, v156
	v_mov_b32_e32 v64, v157
	v_mov_b32_e32 v50, v140
	v_mov_b32_e32 v34, v141

.LBB0_192:
	v_add_f32_e32 v50, 0, v50
	v_add_f32_e32 v34, 0, v34
	v_add_f32_e32 v50, v50, v51
	v_add_f32_e32 v34, v34, v35
	v_add_f32_e32 v35, v52, v50
	v_add_f32_e32 v34, v36, v34
	v_add_f32_e32 v35, v53, v35
	v_add_f32_e32 v34, v37, v34
	v_add_f32_e32 v35, v54, v35
	v_add_f32_e32 v34, v38, v34
	v_add_f32_e32 v35, v55, v35
	v_add_f32_e32 v34, v39, v34
	v_add_f32_e32 v35, v56, v35
	v_add_f32_e32 v34, v40, v34
	v_add_f32_e32 v35, v57, v35
	v_add_f32_e32 v34, v41, v34
	v_add_f32_e32 v35, v58, v35
	v_add_f32_e32 v34, v42, v34
	v_add_f32_e32 v35, v59, v35
	v_add_f32_e32 v34, v43, v34
	v_add_f32_e32 v35, v60, v35
	v_add_f32_e32 v34, v44, v34
	v_add_f32_e32 v35, v61, v35
	v_add_f32_e32 v34, v45, v34
	v_add_f32_e32 v35, v62, v35
	v_add_f32_e32 v34, v46, v34
	ds_read_b128 v[90:93], v135 offset:18432
	ds_read_b128 v[94:97], v135 offset:18464
	ds_read_b128 v[98:101], v135 offset:23040
	ds_read_b128 v[138:141], v135 offset:23072
	v_add_f32_e32 v35, v63, v35
	v_add_f32_e32 v34, v47, v34
	v_add_f32_e32 v35, v64, v35
	v_add_f32_e32 v34, v48, v34
	v_add_f32_e32 v35, v65, v35
	v_add_f32_e32 v34, v49, v34
	v_add_f32_e32 v34, v34, v35
	v_add_f32_e32 v128, v136, v34
	s_waitcnt lgkmcnt(3)
	s_nop 0
	v_mfma_f32_32x32x16_bf16 v[50:65], v[90:93], v[70:73], v[218:233]
	s_waitcnt lgkmcnt(1)
	v_mfma_f32_32x32x16_bf16 v[34:49], v[98:101], v[70:73], v[218:233]
	v_mfma_f32_32x32x16_bf16 v[50:65], v[94:97], v[74:77], v[50:65]
	ds_read_b128 v[118:121], v137 offset:27648
	ds_read_b128 v[114:117], v137 offset:27680
	ds_read_b128 v[110:113], v137 offset:27712
	ds_read_b128 v[106:109], v137 offset:27744
	ds_read_b128 v[102:105], v137 offset:32256
	ds_read_b128 v[98:101], v137 offset:32288
	ds_read_b128 v[90:93], v137 offset:32320
	ds_read_b128 v[94:97], v137 offset:32352
	s_waitcnt lgkmcnt(8)
	v_mfma_f32_32x32x16_bf16 v[34:49], v[138:141], v[74:77], v[34:49]
	s_nop 1
.LBB0_194:
	v_exp_f32_e32 v50, v50
	v_exp_f32_e32 v51, v51
	v_exp_f32_e32 v52, v52
	v_exp_f32_e32 v53, v53
	v_exp_f32_e32 v54, v54
	v_exp_f32_e32 v55, v55
	v_exp_f32_e32 v56, v56
	v_exp_f32_e32 v57, v57
	v_cvt_pk_bf16_f32 v136, v50, v51
	v_cvt_pk_bf16_f32 v137, v52, v53
	v_cvt_pk_bf16_f32 v138, v54, v55
	v_cvt_pk_bf16_f32 v139, v56, v57
	v_exp_f32_e32 v58, v58
	v_exp_f32_e32 v59, v59
	s_waitcnt lgkmcnt(0)
	v_mfma_f32_32x32x16_bf16 v[2:17], v[118:121], v[136:139], v[2:17]
	v_exp_f32_e32 v60, v60
	v_exp_f32_e32 v61, v61
	v_exp_f32_e32 v62, v62
	v_exp_f32_e32 v63, v63
	v_exp_f32_e32 v64, v64
	v_exp_f32_e32 v65, v65
	v_cvt_pk_bf16_f32 v140, v58, v59
	v_mfma_f32_32x32x16_bf16 v[18:33], v[102:105], v[136:139], v[18:33]
	v_cvt_pk_bf16_f32 v141, v60, v61
	v_cvt_pk_bf16_f32 v142, v62, v63
	v_cvt_pk_bf16_f32 v143, v64, v65
	v_exp_f32_e32 v34, v34
	v_exp_f32_e32 v35, v35
	v_exp_f32_e32 v36, v36
	v_exp_f32_e32 v37, v37
	v_mfma_f32_32x32x16_bf16 v[2:17], v[114:117], v[140:143], v[2:17]
	v_exp_f32_e32 v38, v38
	v_exp_f32_e32 v39, v39
	v_exp_f32_e32 v40, v40
	v_exp_f32_e32 v41, v41
	v_cvt_pk_bf16_f32 v144, v34, v35
	v_cvt_pk_bf16_f32 v145, v36, v37
	v_cvt_pk_bf16_f32 v146, v38, v39
	v_mfma_f32_32x32x16_bf16 v[18:33], v[98:101], v[140:143], v[18:33]
	v_cvt_pk_bf16_f32 v147, v40, v41
	v_exp_f32_e32 v42, v42
	v_exp_f32_e32 v43, v43
	v_exp_f32_e32 v44, v44
	v_exp_f32_e32 v45, v45
	v_exp_f32_e32 v46, v46
	v_exp_f32_e32 v47, v47
	v_mfma_f32_32x32x16_bf16 v[2:17], v[110:113], v[144:147], v[2:17]
	v_exp_f32_e32 v48, v48
	v_exp_f32_e32 v49, v49
	v_cvt_pk_bf16_f32 v150, v42, v43
	v_cvt_pk_bf16_f32 v151, v44, v45
	v_cvt_pk_bf16_f32 v152, v46, v47
	v_cvt_pk_bf16_f32 v153, v48, v49
	s_andn2_b64 vcc, exec, s[88:89]
	v_mfma_f32_32x32x16_bf16 v[18:33], v[90:93], v[144:147], v[18:33]
	v_mfma_f32_32x32x16_bf16 v[2:17], v[106:109], v[150:153], v[2:17]
	v_mfma_f32_32x32x16_bf16 v[18:33], v[94:97], v[150:153], v[18:33]
	s_cbranch_vccnz .LBB0_185
	ds_write_b128 v123, v[66:69]
	ds_write_b128 v122, v[78:81] offset:9216
	s_branch .LBB0_185
.LBB0_185_sl:
	v_add_f32_e32 v50, 0, v50
	v_add_f32_e32 v34, 0, v34
	v_add_f32_e32 v50, v50, v51
	v_add_f32_e32 v34, v34, v35
	v_add_f32_e32 v35, v52, v50
	v_add_f32_e32 v34, v36, v34
	v_add_f32_e32 v35, v53, v35
	v_add_f32_e32 v34, v37, v34
	v_add_f32_e32 v35, v54, v35
	v_add_f32_e32 v34, v38, v34
	v_add_f32_e32 v35, v55, v35
	v_add_f32_e32 v34, v39, v34
	v_add_f32_e32 v35, v56, v35
	v_add_f32_e32 v34, v40, v34
	v_add_f32_e32 v35, v57, v35
	v_add_f32_e32 v34, v41, v34
	v_add_f32_e32 v35, v58, v35
	v_add_f32_e32 v34, v42, v34
	v_add_f32_e32 v35, v59, v35
	v_add_f32_e32 v34, v43, v34
	v_add_f32_e32 v35, v60, v35
	v_add_f32_e32 v34, v44, v34
	v_add_f32_e32 v35, v61, v35
	v_add_f32_e32 v34, v45, v34
	v_add_f32_e32 v35, v62, v35
	v_add_f32_e32 v34, v46, v34
	v_add_f32_e32 v35, v63, v35
	v_add_f32_e32 v34, v47, v34
	v_add_f32_e32 v35, v64, v35
	v_add_f32_e32 v34, v48, v34
	v_add_f32_e32 v35, v65, v35
	v_add_f32_e32 v34, v49, v34
	v_add_f32_e32 v34, v34, v35
	s_add_i32 s3, s3, 2
	v_add_f32_e32 v136, v128, v34
	v_lshl_add_u64 v[124:125], v[124:125], 0, s[30:31]
	s_cmp_lt_u32 s12, s2
	v_lshl_add_u64 v[126:127], v[126:127], 0, s[28:29]
	s_waitcnt lgkmcnt(0)
	s_barrier
	s_cbranch_scc0 .LBB0_196

.LBB0_196:
	s_cmp_lg_u32 s98, 0
	s_cbranch_scc1 .Lspec_b_ok
	v_mov_b32_e32 v34, 0x5f800000
	v_cmp_nlt_f32_e32 vcc, v136, v34
	v_mov_b32_e32 v34, 0x24008
	s_cbranch_vccz .Lspec_b_w
	v_mov_b32_e32 v35, 1
	ds_write_b32 v34, v35
.Lspec_b_w:
	s_waitcnt lgkmcnt(0)
	s_barrier
	ds_read_b32 v35, v34
	s_waitcnt lgkmcnt(0)
	s_barrier
	v_readfirstlane_b32 s2, v35
	s_cmp_eq_u32 s2, 0
	s_cbranch_scc1 .Lspec_b_ok
	v_mov_b32_e32 v35, 0
	ds_write_b32 v34, v35
	s_waitcnt lgkmcnt(0)
	s_barrier
	s_mov_b32 s98, 1
	s_mov_b32 s12, s99
	s_branch .Lspec_redo_entry

.LBB0_203:
	s_cmp_lg_u32 s98, 0
	s_cbranch_scc1 .Lspec_c_ok
	v_mov_b32_e32 v2, 0x5f800000
	v_cmp_nlt_f32_e32 vcc, v0, v2
	v_mov_b32_e32 v2, 0x24008
	s_cbranch_vccz .Lspec_c_w
	v_mov_b32_e32 v3, 1
	ds_write_b32 v2, v3
.Lspec_c_w:
	s_waitcnt lgkmcnt(0)
	s_barrier
	ds_read_b32 v3, v2
	s_waitcnt lgkmcnt(0)
	s_barrier
	v_readfirstlane_b32 s2, v3
	s_cmp_eq_u32 s2, 0
	s_cbranch_scc1 .Lspec_c_ok
	v_mov_b32_e32 v3, 0
	ds_write_b32 v2, v3
	s_waitcnt lgkmcnt(0)
	s_barrier
	s_mov_b32 s98, 1
	s_mov_b32 s12, s99
	s_branch .Lspec_redo_entry
